# P7 K-loop first iteration peeled: first-touch MFMAs use inline 0 SrcC, per-unit accumulator zeroing (128 v_mov) removed
# speedup vs baseline: 1.0310x; 1.0034x over previous
; #define PG8_STAGE(bufoff, gbase, voff) do { _Pragma("unroll") for (int _i = 0; _i < 2; ++_i) \
;         __builtin_amdgcn_global_load_lds((const unsigned*)((const char*)(gbase) + (voff)[_i]), (LAS unsigned*)(lds + (bufoff) + ldsw + _i * 8192), 16, 0, 0); } while (0)
; #define PG8_LDA(dst, b, h) do { _Pragma("unroll") for (int m = 0; m < 4; ++m) _Pragma("unroll") for (int k = 0; k < 2; ++k) dst[m][k] = *(const LAS bf16x8*)(lds + PG8_SA(b, h) + aoff + m * 2048 + k * 1024); } while (0)
; #define PG8_LDB(dst, b, h) do { _Pragma("unroll") for (int n = 0; n < 2; ++n) _Pragma("unroll") for (int k = 0; k < 2; ++k) dst[n][k] = *(const LAS bf16x8*)(lds + PG8_SB(b, h) + boff + n * 2048 + k * 1024); } while (0)
; #define PG8_MMA(ai, bj, At, Bt) do { __builtin_amdgcn_s_setprio(1); _Pragma("unroll") for (int m = 0; m < 4; ++m) _Pragma("unroll") for (int n = 0; n < 2; ++n) _Pragma("unroll") for (int k = 0; k < 2; ++k) \
;         acc[ai][bj][m][n] = __builtin_amdgcn_mfma_f32_16x16x32_bf16(Bt[n][k], At[m][k], acc[ai][bj][m][n], 0, 0, 0); __builtin_amdgcn_s_setprio(0); } while (0)
; #define PG8_WAIT_L(n) asm volatile("s_waitcnt lgkmcnt(" #n ")" ::: "memory")
; #define PG8_BAR __builtin_amdgcn_s_barrier()
; #define PG8_SCHED __builtin_amdgcn_sched_barrier(0)
; template <class Epi, class Sched>
; __device__ __forceinline__ void gemm_phase(LAS unsigned char* lds, const int K, const Sched& S, const Epi& E) {
;     ...
;             PG8_LDB(B0, 0, 0); PG8_SCHED; PG8_LDA(At, 0, 0); PG8_STAGE(PG8_SA(1, 1), a1 + hstepA, voffA);
;             PG8_WAIT_L(8); PG8_BAR; PG8_WAIT_L(0); PG8_MMA(0, 0, At, B0); PG8_BAR; PG8_SCHED;
;             PG8_LDB(B1, 0, 1); PG8_STAGE(PG8_SB(0, 0), b2, voffB);
;             PG8_BAR; PG8_WAIT_L(0); PG8_MMA(0, 1, At, B1); PG8_BAR;
;             PG8_LDA(At, 0, 1); PG8_STAGE(PG8_SA(0, 0), a2, voffA);
;             PG8_BAR; PG8_WAIT_L(0); PG8_MMA(1, 0, At, B0); PG8_BAR; PG8_SCHED;
;     ...
;                     for (int n = 0; n < 2; ++n) acc[a][b][m][n] = (f32x4){0.f, 0.f, 0.f, 0.f};
.LBB0_799:
	v_lshl_or_b32 v253, s10, 7, v157
	v_lshlrev_b32_e32 v253, 2, v253
	global_load_dwordx4 v[224:227], v253, s[22:23]
	global_load_dwordx4 v[228:231], v253, s[24:25]
	global_load_dwordx4 v[232:235], v253, s[26:27]
	global_load_dwordx4 v[236:239], v253, s[36:37]
	s_add_u32 s11, s68, 0x100
	s_addc_u32 s33, s69, 0
	s_mov_b32 s49, -2
	s_waitcnt lgkmcnt(0)
.Lpeel_p7:
	ds_read_b128 v[128:131], v158
	ds_read_b128 v[132:135], v158 offset:1024
	ds_read_b128 v[148:151], v158 offset:2048
	ds_read_b128 v[162:165], v158 offset:3072
	s_add_u32 s68, s12, 0x100
	s_addc_u32 s69, s13, 0
	s_cmp_eq_u32 s49, 12
	s_cselect_b32 s73, s63, s69
	s_cselect_b32 s72, s62, s68
	s_cselect_b32 s71, s65, s33
	s_cselect_b32 s70, s64, s11
	v_lshl_add_u64 v[200:201], s[12:13], 0, v[144:145]
	s_add_i32 m0, s67, 0xc000
	ds_read_b128 v[166:169], v159
	ds_read_b128 v[172:175], v159 offset:1024
	ds_read_b128 v[176:179], v159 offset:2048
	ds_read_b128 v[180:183], v159 offset:3072
	ds_read_b128 v[184:187], v159 offset:4096
	ds_read_b128 v[188:191], v159 offset:5120
	ds_read_b128 v[192:195], v159 offset:6144
	ds_read_b128 v[196:199], v159 offset:7168
	global_load_lds_dwordx4 v[200:201], off
	v_lshl_add_u64 v[200:201], s[12:13], 0, v[146:147]
	s_add_i32 m0, s67, 0xe000
	s_nop 0
	global_load_lds_dwordx4 v[200:201], off
	s_waitcnt lgkmcnt(8)
	s_barrier
	s_waitcnt lgkmcnt(0)
	s_setprio 1
	s_waitcnt lgkmcnt(0)
	v_mfma_f32_16x16x32_bf16 v[84:87], v[128:131], v[166:169], 0
	v_mfma_f32_16x16x32_bf16 v[76:79], v[148:151], v[166:169], 0
	v_mfma_f32_16x16x32_bf16 v[124:127], v[128:131], v[176:179], 0
	v_mfma_f32_16x16x32_bf16 v[72:75], v[148:151], v[176:179], 0
	v_mfma_f32_16x16x32_bf16 v[120:123], v[128:131], v[184:187], 0
	v_mfma_f32_16x16x32_bf16 v[96:99], v[148:151], v[184:187], 0
	v_mfma_f32_16x16x32_bf16 v[116:119], v[128:131], v[192:195], 0
	v_mfma_f32_16x16x32_bf16 v[92:95], v[148:151], v[192:195], 0
	v_mfma_f32_16x16x32_bf16 v[84:87], v[132:135], v[172:175], v[84:87]
	v_mfma_f32_16x16x32_bf16 v[76:79], v[162:165], v[172:175], v[76:79]
	v_mfma_f32_16x16x32_bf16 v[124:127], v[132:135], v[180:183], v[124:127]
	v_mfma_f32_16x16x32_bf16 v[72:75], v[162:165], v[180:183], v[72:75]
	v_mfma_f32_16x16x32_bf16 v[120:123], v[132:135], v[188:191], v[120:123]
	v_mfma_f32_16x16x32_bf16 v[96:99], v[162:165], v[188:191], v[96:99]
	v_mfma_f32_16x16x32_bf16 v[116:119], v[132:135], v[196:199], v[116:119]
	v_mfma_f32_16x16x32_bf16 v[92:95], v[162:165], v[196:199], v[92:95]
	s_setprio 0
	s_barrier
	s_add_i32 s12, s88, s78
	v_lshl_add_u64 v[216:217], s[70:71], 0, v[138:139]
	s_mov_b32 m0, s12
	ds_read_b128 v[200:203], v160
	ds_read_b128 v[204:207], v160 offset:1024
	ds_read_b128 v[208:211], v160 offset:2048
	ds_read_b128 v[212:215], v160 offset:3072
	global_load_lds_dwordx4 v[216:217], off
	v_lshl_add_u64 v[218:219], s[70:71], 0, v[142:143]
	s_add_i32 m0, s12, 0x2000
	s_nop 0
	global_load_lds_dwordx4 v[218:219], off
	s_barrier
	s_waitcnt lgkmcnt(0)
	s_setprio 1
	s_waitcnt lgkmcnt(0)
	v_mfma_f32_16x16x32_bf16 v[60:63], v[200:203], v[166:169], 0
	v_mfma_f32_16x16x32_bf16 v[16:19], v[208:211], v[166:169], 0
	v_mfma_f32_16x16x32_bf16 v[56:59], v[200:203], v[176:179], 0
	v_mfma_f32_16x16x32_bf16 v[12:15], v[208:211], v[176:179], 0
	v_mfma_f32_16x16x32_bf16 v[52:55], v[200:203], v[184:187], 0
	v_mfma_f32_16x16x32_bf16 v[28:31], v[208:211], v[184:187], 0
	v_mfma_f32_16x16x32_bf16 v[48:51], v[200:203], v[192:195], 0
	v_mfma_f32_16x16x32_bf16 v[24:27], v[208:211], v[192:195], 0
	v_mfma_f32_16x16x32_bf16 v[60:63], v[204:207], v[172:175], v[60:63]
	v_mfma_f32_16x16x32_bf16 v[16:19], v[212:215], v[172:175], v[16:19]
	v_mfma_f32_16x16x32_bf16 v[56:59], v[204:207], v[180:183], v[56:59]
	v_mfma_f32_16x16x32_bf16 v[12:15], v[212:215], v[180:183], v[12:15]
	v_mfma_f32_16x16x32_bf16 v[52:55], v[204:207], v[188:191], v[52:55]
	v_mfma_f32_16x16x32_bf16 v[28:31], v[212:215], v[188:191], v[28:31]
	v_mfma_f32_16x16x32_bf16 v[48:51], v[204:207], v[196:199], v[48:51]
	v_mfma_f32_16x16x32_bf16 v[24:27], v[212:215], v[196:199], v[24:27]
	s_setprio 0
	s_mov_b32 m0, s67
	v_lshl_add_u64 v[220:221], s[72:73], 0, v[136:137]
	s_barrier
	ds_read_b128 v[166:169], v159 offset:16384
	ds_read_b128 v[172:175], v159 offset:17408
	ds_read_b128 v[176:179], v159 offset:18432
	ds_read_b128 v[180:183], v159 offset:19456
	ds_read_b128 v[184:187], v159 offset:20480
	ds_read_b128 v[188:191], v159 offset:21504
	ds_read_b128 v[192:195], v159 offset:22528
	ds_read_b128 v[196:199], v159 offset:23552
	global_load_lds_dwordx4 v[220:221], off
	v_lshl_add_u64 v[222:223], s[72:73], 0, v[140:141]
	s_mov_b32 m0, s80
	s_nop 0
	global_load_lds_dwordx4 v[222:223], off
	s_barrier
	s_waitcnt lgkmcnt(0)
	s_setprio 1
	s_waitcnt lgkmcnt(0)
	v_mfma_f32_16x16x32_bf16 v[112:115], v[128:131], v[166:169], 0
	v_mfma_f32_16x16x32_bf16 v[88:91], v[148:151], v[166:169], 0
	v_mfma_f32_16x16x32_bf16 v[104:107], v[128:131], v[176:179], 0
	v_mfma_f32_16x16x32_bf16 v[80:83], v[148:151], v[176:179], 0
	v_mfma_f32_16x16x32_bf16 v[100:103], v[128:131], v[184:187], 0
	v_mfma_f32_16x16x32_bf16 v[64:67], v[148:151], v[184:187], 0
	v_mfma_f32_16x16x32_bf16 v[108:111], v[128:131], v[192:195], 0
	v_mfma_f32_16x16x32_bf16 v[68:71], v[148:151], v[192:195], 0
	v_mfma_f32_16x16x32_bf16 v[112:115], v[132:135], v[172:175], v[112:115]
	v_mfma_f32_16x16x32_bf16 v[88:91], v[162:165], v[172:175], v[88:91]
	v_mfma_f32_16x16x32_bf16 v[104:107], v[132:135], v[180:183], v[104:107]
	v_mfma_f32_16x16x32_bf16 v[80:83], v[162:165], v[180:183], v[80:83]
	v_mfma_f32_16x16x32_bf16 v[100:103], v[132:135], v[188:191], v[100:103]
	v_mfma_f32_16x16x32_bf16 v[64:67], v[162:165], v[188:191], v[64:67]
	v_mfma_f32_16x16x32_bf16 v[108:111], v[132:135], v[196:199], v[108:111]
	v_mfma_f32_16x16x32_bf16 v[68:71], v[162:165], v[196:199], v[68:71]
	s_setprio 0
	s_barrier
; #define PG8_STAGE(bufoff, gbase, voff) do { _Pragma("unroll") for (int _i = 0; _i < 2; ++_i) \
;         __builtin_amdgcn_global_load_lds((const unsigned*)((const char*)(gbase) + (voff)[_i]), (LAS unsigned*)(lds + (bufoff) + ldsw + _i * 8192), 16, 0, 0); } while (0)
; #define PG8_LDA(dst, b, h) do { _Pragma("unroll") for (int m = 0; m < 4; ++m) _Pragma("unroll") for (int k = 0; k < 2; ++k) dst[m][k] = *(const LAS bf16x8*)(lds + PG8_SA(b, h) + aoff + m * 2048 + k * 1024); } while (0)
; #define PG8_LDB(dst, b, h) do { _Pragma("unroll") for (int n = 0; n < 2; ++n) _Pragma("unroll") for (int k = 0; k < 2; ++k) dst[n][k] = *(const LAS bf16x8*)(lds + PG8_SB(b, h) + boff + n * 2048 + k * 1024); } while (0)
; #define PG8_MMA(ai, bj, At, Bt) do { __builtin_amdgcn_s_setprio(1); _Pragma("unroll") for (int m = 0; m < 4; ++m) _Pragma("unroll") for (int n = 0; n < 2; ++n) _Pragma("unroll") for (int k = 0; k < 2; ++k) \
;         acc[ai][bj][m][n] = __builtin_amdgcn_mfma_f32_16x16x32_bf16(Bt[n][k], At[m][k], acc[ai][bj][m][n], 0, 0, 0); __builtin_amdgcn_s_setprio(0); } while (0)
; #define PG8_WAIT_V(n) asm volatile("s_waitcnt vmcnt(" #n ")" ::: "memory")
; #define PG8_WAIT_L(n) asm volatile("s_waitcnt lgkmcnt(" #n ")" ::: "memory")
; #define PG8_BAR __builtin_amdgcn_s_barrier()
; #define PG8_SCHED __builtin_amdgcn_sched_barrier(0)
; template <class Epi, class Sched>
; __device__ __forceinline__ void gemm_phase(LAS unsigned char* lds, const int K, const Sched& S, const Epi& E) {
;     ...
;             PG8_STAGE(PG8_SB(0, 1), b2 + hstep, voffB);
;             PG8_WAIT_V(6); PG8_BAR; PG8_MMA(1, 1, At, B1); PG8_BAR;
;             PG8_LDB(B0, 1, 0); PG8_SCHED; PG8_LDA(At, 1, 0); PG8_STAGE(PG8_SA(0, 1), a2 + hstepA, voffA);
;             PG8_WAIT_L(8); PG8_BAR; PG8_WAIT_L(0); PG8_MMA(0, 0, At, B0); PG8_BAR; PG8_SCHED;
;             PG8_LDB(B1, 1, 1); PG8_STAGE(PG8_SB(1, 0), b3, voffB);
;             PG8_BAR; PG8_WAIT_L(0); PG8_MMA(0, 1, At, B1); PG8_BAR;
	s_add_u32 s12, s70, 0x40000
	s_addc_u32 s13, s71, 0
	s_add_i32 s52, s89, s78
	v_lshl_add_u64 v[128:129], s[12:13], 0, v[138:139]
	s_mov_b32 m0, s52
	s_nop 0
	global_load_lds_dwordx4 v[128:129], off
	v_lshl_add_u64 v[128:129], s[12:13], 0, v[142:143]
	s_add_i32 m0, s52, 0x2000
	s_nop 0
	global_load_lds_dwordx4 v[128:129], off
	s_waitcnt vmcnt(6)
	s_barrier
	s_setprio 1
	v_mfma_f32_16x16x32_bf16 v[44:47], v[200:203], v[166:169], 0
	v_mfma_f32_16x16x32_bf16 v[20:23], v[208:211], v[166:169], 0
	v_mfma_f32_16x16x32_bf16 v[40:43], v[200:203], v[176:179], 0
	v_mfma_f32_16x16x32_bf16 v[8:11], v[208:211], v[176:179], 0
	v_mfma_f32_16x16x32_bf16 v[36:39], v[200:203], v[184:187], 0
	v_mfma_f32_16x16x32_bf16 v[0:3], v[208:211], v[184:187], 0
	v_mfma_f32_16x16x32_bf16 v[32:35], v[200:203], v[192:195], 0
	v_mfma_f32_16x16x32_bf16 v[4:7], v[208:211], v[192:195], 0
	v_mfma_f32_16x16x32_bf16 v[44:47], v[204:207], v[172:175], v[44:47]
	v_mfma_f32_16x16x32_bf16 v[20:23], v[212:215], v[172:175], v[20:23]
	v_mfma_f32_16x16x32_bf16 v[40:43], v[204:207], v[180:183], v[40:43]
	v_mfma_f32_16x16x32_bf16 v[8:11], v[212:215], v[180:183], v[8:11]
	v_mfma_f32_16x16x32_bf16 v[36:39], v[204:207], v[188:191], v[36:39]
	v_mfma_f32_16x16x32_bf16 v[0:3], v[212:215], v[188:191], v[0:3]
	v_mfma_f32_16x16x32_bf16 v[32:35], v[204:207], v[196:199], v[32:35]
	v_mfma_f32_16x16x32_bf16 v[4:7], v[212:215], v[196:199], v[4:7]
	s_setprio 0
	s_add_i32 s52, 0, 0x18000
	v_add_u32_e32 v161, s52, v156
	s_barrier
	ds_read_b128 v[128:131], v161
	ds_read_b128 v[132:135], v161 offset:1024
	ds_read_b128 v[148:151], v161 offset:2048
	ds_read_b128 v[162:165], v161 offset:3072
	s_add_u32 s12, s72, 0x20000
	s_addc_u32 s13, s73, 0
	s_mov_b32 m0, s81
	v_lshl_add_u64 v[200:201], s[12:13], 0, v[136:137]
	ds_read_b128 v[166:169], v159 offset:32768
	ds_read_b128 v[172:175], v159 offset:33792
	ds_read_b128 v[176:179], v159 offset:34816
	ds_read_b128 v[180:183], v159 offset:35840
	ds_read_b128 v[184:187], v159 offset:36864
	ds_read_b128 v[188:191], v159 offset:37888
	ds_read_b128 v[192:195], v159 offset:38912
	ds_read_b128 v[196:199], v159 offset:39936
	global_load_lds_dwordx4 v[200:201], off
	v_lshl_add_u64 v[200:201], s[12:13], 0, v[140:141]
	s_mov_b32 m0, s82
	s_nop 0
	global_load_lds_dwordx4 v[200:201], off
	s_waitcnt lgkmcnt(8)
	s_barrier
	s_waitcnt lgkmcnt(0)
	s_setprio 1
	s_waitcnt lgkmcnt(0)
	v_mfma_f32_16x16x32_bf16 v[84:87], v[128:131], v[166:169], v[84:87]
	v_mfma_f32_16x16x32_bf16 v[76:79], v[148:151], v[166:169], v[76:79]
	v_mfma_f32_16x16x32_bf16 v[124:127], v[128:131], v[176:179], v[124:127]
	v_mfma_f32_16x16x32_bf16 v[72:75], v[148:151], v[176:179], v[72:75]
	v_mfma_f32_16x16x32_bf16 v[120:123], v[128:131], v[184:187], v[120:123]
	v_mfma_f32_16x16x32_bf16 v[96:99], v[148:151], v[184:187], v[96:99]
	v_mfma_f32_16x16x32_bf16 v[116:119], v[128:131], v[192:195], v[116:119]
	v_mfma_f32_16x16x32_bf16 v[92:95], v[148:151], v[192:195], v[92:95]
	v_mfma_f32_16x16x32_bf16 v[84:87], v[132:135], v[172:175], v[84:87]
	v_mfma_f32_16x16x32_bf16 v[76:79], v[162:165], v[172:175], v[76:79]
	v_mfma_f32_16x16x32_bf16 v[124:127], v[132:135], v[180:183], v[124:127]
	v_mfma_f32_16x16x32_bf16 v[72:75], v[162:165], v[180:183], v[72:75]
	v_mfma_f32_16x16x32_bf16 v[120:123], v[132:135], v[188:191], v[120:123]
	v_mfma_f32_16x16x32_bf16 v[96:99], v[162:165], v[188:191], v[96:99]
	v_mfma_f32_16x16x32_bf16 v[116:119], v[132:135], v[196:199], v[116:119]
	v_mfma_f32_16x16x32_bf16 v[92:95], v[162:165], v[196:199], v[92:95]
	s_setprio 0
	s_barrier
	s_add_i32 s53, 0, 0x1c000
	s_add_i32 s12, s52, s78
	v_add_u32_e32 v161, s53, v156
	v_lshl_add_u64 v[216:217], v[216:217], 0, s[38:39]
	s_mov_b32 m0, s12
	ds_read_b128 v[200:203], v161
	ds_read_b128 v[204:207], v161 offset:1024
	ds_read_b128 v[208:211], v161 offset:2048
	ds_read_b128 v[212:215], v161 offset:3072
	global_load_lds_dwordx4 v[216:217], off
	v_lshl_add_u64 v[216:217], v[218:219], 0, s[38:39]
	s_add_i32 m0, s12, 0x2000
	s_nop 0
	global_load_lds_dwordx4 v[216:217], off
	s_barrier
; #define PG8_STAGE(bufoff, gbase, voff) do { _Pragma("unroll") for (int _i = 0; _i < 2; ++_i) \
;         __builtin_amdgcn_global_load_lds((const unsigned*)((const char*)(gbase) + (voff)[_i]), (LAS unsigned*)(lds + (bufoff) + ldsw + _i * 8192), 16, 0, 0); } while (0)
; #define PG8_LDA(dst, b, h) do { _Pragma("unroll") for (int m = 0; m < 4; ++m) _Pragma("unroll") for (int k = 0; k < 2; ++k) dst[m][k] = *(const LAS bf16x8*)(lds + PG8_SA(b, h) + aoff + m * 2048 + k * 1024); } while (0)
; #define PG8_MMA(ai, bj, At, Bt) do { __builtin_amdgcn_s_setprio(1); _Pragma("unroll") for (int m = 0; m < 4; ++m) _Pragma("unroll") for (int n = 0; n < 2; ++n) _Pragma("unroll") for (int k = 0; k < 2; ++k) \
;         acc[ai][bj][m][n] = __builtin_amdgcn_mfma_f32_16x16x32_bf16(Bt[n][k], At[m][k], acc[ai][bj][m][n], 0, 0, 0); __builtin_amdgcn_s_setprio(0); } while (0)
; #define PG8_WAIT_V(n) asm volatile("s_waitcnt vmcnt(" #n ")" ::: "memory")
; #define PG8_WAIT_L(n) asm volatile("s_waitcnt lgkmcnt(" #n ")" ::: "memory")
; #define PG8_BAR __builtin_amdgcn_s_barrier()
; #define PG8_SCHED __builtin_amdgcn_sched_barrier(0)
; template <class Epi, class Sched>
; __device__ __forceinline__ void gemm_phase(LAS unsigned char* lds, const int K, const Sched& S, const Epi& E) {
;     ...
;             PG8_BAR; PG8_WAIT_L(0); PG8_MMA(0, 1, At, B1); PG8_BAR;
;             PG8_LDA(At, 1, 1); PG8_STAGE(PG8_SA(1, 0), a3, voffA);
;             PG8_BAR; PG8_WAIT_L(0); PG8_MMA(1, 0, At, B0); PG8_BAR; PG8_SCHED;
;             PG8_STAGE(PG8_SB(1, 1), b3 + hstep, voffB);
;             PG8_WAIT_V(6); PG8_BAR; PG8_MMA(1, 1, At, B1); PG8_BAR;
	s_waitcnt lgkmcnt(0)
	s_setprio 1
	s_waitcnt lgkmcnt(0)
	v_mfma_f32_16x16x32_bf16 v[60:63], v[200:203], v[166:169], v[60:63]
	v_mfma_f32_16x16x32_bf16 v[16:19], v[208:211], v[166:169], v[16:19]
	v_mfma_f32_16x16x32_bf16 v[56:59], v[200:203], v[176:179], v[56:59]
	v_mfma_f32_16x16x32_bf16 v[12:15], v[208:211], v[176:179], v[12:15]
	v_mfma_f32_16x16x32_bf16 v[52:55], v[200:203], v[184:187], v[52:55]
	v_mfma_f32_16x16x32_bf16 v[28:31], v[208:211], v[184:187], v[28:31]
	v_mfma_f32_16x16x32_bf16 v[48:51], v[200:203], v[192:195], v[48:51]
	v_mfma_f32_16x16x32_bf16 v[24:27], v[208:211], v[192:195], v[24:27]
	v_mfma_f32_16x16x32_bf16 v[60:63], v[204:207], v[172:175], v[60:63]
	v_mfma_f32_16x16x32_bf16 v[16:19], v[212:215], v[172:175], v[16:19]
	v_mfma_f32_16x16x32_bf16 v[56:59], v[204:207], v[180:183], v[56:59]
	v_mfma_f32_16x16x32_bf16 v[12:15], v[212:215], v[180:183], v[12:15]
	v_mfma_f32_16x16x32_bf16 v[52:55], v[204:207], v[188:191], v[52:55]
	v_mfma_f32_16x16x32_bf16 v[28:31], v[212:215], v[188:191], v[28:31]
	v_mfma_f32_16x16x32_bf16 v[48:51], v[204:207], v[196:199], v[48:51]
	v_mfma_f32_16x16x32_bf16 v[24:27], v[212:215], v[196:199], v[24:27]
	s_setprio 0
	s_mov_b32 m0, s84
	v_lshl_add_u64 v[216:217], v[220:221], 0, s[38:39]
	s_barrier
	ds_read_b128 v[166:169], v159 offset:49152
	ds_read_b128 v[172:175], v159 offset:50176
	ds_read_b128 v[176:179], v159 offset:51200
	ds_read_b128 v[180:183], v159 offset:52224
	ds_read_b128 v[184:187], v159 offset:53248
	ds_read_b128 v[188:191], v159 offset:54272
	ds_read_b128 v[192:195], v159 offset:55296
	ds_read_b128 v[196:199], v159 offset:56320
	global_load_lds_dwordx4 v[216:217], off
	v_lshl_add_u64 v[216:217], v[222:223], 0, s[38:39]
	s_mov_b32 m0, s85
	s_nop 0
	global_load_lds_dwordx4 v[216:217], off
	s_barrier
	s_waitcnt lgkmcnt(0)
	s_setprio 1
	s_waitcnt lgkmcnt(0)
	v_mfma_f32_16x16x32_bf16 v[112:115], v[128:131], v[166:169], v[112:115]
	v_mfma_f32_16x16x32_bf16 v[88:91], v[148:151], v[166:169], v[88:91]
	v_mfma_f32_16x16x32_bf16 v[104:107], v[128:131], v[176:179], v[104:107]
	v_mfma_f32_16x16x32_bf16 v[80:83], v[148:151], v[176:179], v[80:83]
	v_mfma_f32_16x16x32_bf16 v[100:103], v[128:131], v[184:187], v[100:103]
	v_mfma_f32_16x16x32_bf16 v[64:67], v[148:151], v[184:187], v[64:67]
	v_mfma_f32_16x16x32_bf16 v[108:111], v[128:131], v[192:195], v[108:111]
	v_mfma_f32_16x16x32_bf16 v[68:71], v[148:151], v[192:195], v[68:71]
	v_mfma_f32_16x16x32_bf16 v[112:115], v[132:135], v[172:175], v[112:115]
	v_mfma_f32_16x16x32_bf16 v[88:91], v[162:165], v[172:175], v[88:91]
	v_mfma_f32_16x16x32_bf16 v[104:107], v[132:135], v[180:183], v[104:107]
	v_mfma_f32_16x16x32_bf16 v[80:83], v[162:165], v[180:183], v[80:83]
	v_mfma_f32_16x16x32_bf16 v[100:103], v[132:135], v[188:191], v[100:103]
	v_mfma_f32_16x16x32_bf16 v[64:67], v[162:165], v[188:191], v[64:67]
	v_mfma_f32_16x16x32_bf16 v[108:111], v[132:135], v[196:199], v[108:111]
	v_mfma_f32_16x16x32_bf16 v[68:71], v[162:165], v[196:199], v[68:71]
	s_setprio 0
	s_barrier
	s_add_u32 s12, s70, 0x40080
	s_addc_u32 s13, s71, 0
	s_add_i32 s52, s53, s78
	v_lshl_add_u64 v[128:129], s[12:13], 0, v[138:139]
	s_mov_b32 m0, s52
	s_nop 0
	global_load_lds_dwordx4 v[128:129], off
	v_lshl_add_u64 v[128:129], s[12:13], 0, v[142:143]
	s_add_i32 m0, s52, 0x2000
	s_nop 0
	global_load_lds_dwordx4 v[128:129], off
	s_waitcnt vmcnt(6)
	s_barrier
	s_setprio 1
	v_mfma_f32_16x16x32_bf16 v[44:47], v[200:203], v[166:169], v[44:47]
	v_mfma_f32_16x16x32_bf16 v[20:23], v[208:211], v[166:169], v[20:23]
	v_mfma_f32_16x16x32_bf16 v[40:43], v[200:203], v[176:179], v[40:43]
	v_mfma_f32_16x16x32_bf16 v[8:11], v[208:211], v[176:179], v[8:11]
	v_mfma_f32_16x16x32_bf16 v[36:39], v[200:203], v[184:187], v[36:39]
	v_mfma_f32_16x16x32_bf16 v[0:3], v[208:211], v[184:187], v[0:3]
	v_mfma_f32_16x16x32_bf16 v[32:35], v[200:203], v[192:195], v[32:35]
	v_mfma_f32_16x16x32_bf16 v[4:7], v[208:211], v[192:195], v[4:7]
	v_mfma_f32_16x16x32_bf16 v[44:47], v[204:207], v[172:175], v[44:47]
	v_mfma_f32_16x16x32_bf16 v[20:23], v[212:215], v[172:175], v[20:23]
	v_mfma_f32_16x16x32_bf16 v[40:43], v[204:207], v[180:183], v[40:43]
	v_mfma_f32_16x16x32_bf16 v[8:11], v[212:215], v[180:183], v[8:11]
	v_mfma_f32_16x16x32_bf16 v[36:39], v[204:207], v[188:191], v[36:39]
	v_mfma_f32_16x16x32_bf16 v[0:3], v[212:215], v[188:191], v[0:3]
	v_mfma_f32_16x16x32_bf16 v[32:35], v[204:207], v[196:199], v[32:35]
	v_mfma_f32_16x16x32_bf16 v[4:7], v[212:215], v[196:199], v[4:7]
	s_setprio 0
	s_add_i32 s49, s49, 2
	s_add_u32 s11, s11, 0x100
	s_addc_u32 s33, s33, 0
	s_cmp_gt_u32 s49, 13
	s_mov_b64 s[12:13], s[68:69]
	s_barrier
